# variant: fast loop with the row sums kept on the MFMA (ones operand) as in the baseline instead of f32 VALU adds; otherwise the same structure
# baseline (speedup 1.0000x reference)
; __device__ __forceinline__ void att_qs(bf16x8 (&pn)[4], f32x16 (&o)[4], f32x16& osum, f32x16& negm, const bf16x8 (&qf)[4], float& m_hat, ...
;     __builtin_amdgcn_s_setprio(1);
;     f32x16 c0, c1;
;     bf16x8 kf[4];
;     ...
;     kf[0] = ATT_KREAD(0); kf[1] = ATT_KREAD(1); kf[2] = ATT_KREAD(2); kf[3] = ATT_KREAD(3);
;     __builtin_amdgcn_sched_barrier(0);
; #pragma unroll
;     for (int i = 0; i < 8; ++i) {
;         if (i == 0) c0 = __builtin_amdgcn_mfma_f32_32x32x16_bf16(kf[0], qf[0], negm, 0, 0, 0);
;         else if (i == 1) c1 = __builtin_amdgcn_mfma_f32_32x32x16_bf16(kf[1], qf[0], negm, 0, 0, 0);
;         else if ((i & 1) == 0) c0 = __builtin_amdgcn_mfma_f32_32x32x16_bf16(kf[i & 3], qf[i >> 1], c0, 0, 0, 0);
;         else c1 = __builtin_amdgcn_mfma_f32_32x32x16_bf16(kf[i & 3], qf[i >> 1], c1, 0, 0, 0);
;         if (i + 4 < 8) kf[i & 3] = ATT_KREAD(i + 4);
;         __builtin_amdgcn_sched_barrier(0);
;     }
;     ...
;     if (near) {
; #pragma unroll
;         for (int r = 0; r < 16; ++r) { int i0 = lutbase + crow(r, hi), i1 = i0 + 32; i0 = i0 < 0 ? 0 : (i0 > 255 ? 255 : i0); i1 = i1 < 0 ? 0 : (i1 > 255 ? 255 : i1); c0[r] += lut[i0]; c1[r] += lut[i1]; }
;     }
;     if (first_tile) {
; #pragma unroll
;         for (int r = 0; r < 16; ++r) { if (crow(r, hi) >= NMETA) c0[r] = -INFINITY; c1[r] = -INFINITY; }
;     }
;     asm volatile("s_nop 15\n\ts_nop 7" : "+v"(c0), "+v"(c1));
;     float rm;
;     { float a = max3a(c0[0], c0[1], c0[2]), b = max3a(c1[0], c1[1], c1[2]);
; #pragma unroll
;       for (int r = 3; r < 15; r += 2) { a = max3a(a, c0[r], c0[r + 1]); b = max3a(b, c1[r], c1[r + 1]); }
;       rm = max3a(a, b, c0[15]); rm = max3a(rm, c1[15], c1[15]); }
;     rm = xhalf_max(rm);
;     if (first_tile) {
;         m_hat += rm;
; #pragma unroll
;         for (int r = 0; r < 16; ++r) { c0[r] -= rm; c1[r] -= rm; negm[r] = -m_hat; }
;     } else if (__any(rm > 8.0f)) {
;         const float dl = fmaxf(rm, 0.f); m_hat += dl; const float f = __builtin_amdgcn_exp2f(-dl);
; #pragma unroll
;         for (int r = 0; r < 16; ++r) { c0[r] -= dl; c1[r] -= dl; negm[r] = -m_hat; }
;         if (hi == 0) scr[i32] = f;
;         asm volatile("s_waitcnt lgkmcnt(0)" ::: "memory");
; #pragma unroll
;         for (int r = 0; r < 16; ++r) { const float fr_ = scr[crow(r, hi)]; osum[r] *= fr_;
; #pragma unroll
;             for (int d = 0; d < 4; ++d) o[d][r] *= fr_; }
;     }
.Latt_fast_entry:
	v_mov_b32_e32 v242, s8
	v_mov_b32_e32 v243, s8
	v_mov_b32_e32 v244, s8
	v_mov_b32_e32 v245, s8
	v_mov_b32_e32 v248, v17
	v_mov_b32_e32 v118, v16
	v_readfirstlane_b32 s98, v178
	v_readfirstlane_b32 s99, v179
	v_readfirstlane_b32 s101, v180
	s_nop 3
	s_sub_u32 s101, s101, s98
	s_mov_b32 s100, 0
	s_add_i32 s10, s57, 0xffff4000
	s_and_b32 s10, s10, 0xc000
	v_add_u32_e32 v133, s10, v185
	s_add_i32 s9, s57, 0xffff8000
	s_and_b32 s9, s9, 0xc000
	v_add_u32_e32 v132, s9, v177
	ds_read_b128 v[128:131], v132
	ds_read_b128 v[138:141], v132 offset:2048
	ds_read_b128 v[142:145], v132 offset:4096
	ds_read_b128 v[250:253], v132 offset:6144
	s_add_i32 s9, s56, 2
	s_min_u32 s9, s9, s52
	s_lshl_b32 s10, s9, 14
	s_mov_b32 s11, 0
	s_add_u32 s10, s98, s10
	s_addc_u32 s11, s99, 0
	s_and_b32 s9, s57, 0xc000
	s_add_i32 s9, s9, s53
	s_mov_b32 m0, s9
	s_nop 0
	global_load_lds_dwordx4 v166, s[10:11]
	s_add_u32 s10, s10, 0x2000
	s_addc_u32 s11, s11, 0
	s_add_i32 m0, s9, 0x2000
	s_nop 0
	global_load_lds_dwordx4 v166, s[10:11]
	s_add_i32 s9, s56, 2
	s_min_u32 s9, s9, s52
	s_lshl_b32 s58, s9, 14
	s_and_b32 s59, s57, 0xc000
	s_add_i32 s59, s59, s53
	s_add_i32 s9, s56, 3
	s_min_u32 s9, s9, s52
	s_lshl_b32 s10, s9, 14
	s_mov_b32 s11, 0
	s_add_u32 s10, s98, s10
	s_addc_u32 s11, s99, 0
	s_add_i32 s9, s57, 0x4000
	s_and_b32 s9, s9, 0xc000
	s_add_i32 s9, s9, s53
	s_waitcnt lgkmcnt(3)
	v_mfma_f32_32x32x16_bf16 v[226:241], v[128:131], v[146:149], v[98:113]
	ds_read_b128 v[128:131], v132 offset:512
	s_waitcnt lgkmcnt(3)
	v_mfma_f32_32x32x16_bf16 v[226:241], v[138:141], v[150:153], v[226:241]
	ds_read_b128 v[138:141], v132 offset:2560
	s_waitcnt lgkmcnt(3)
	v_mfma_f32_32x32x16_bf16 v[226:241], v[142:145], v[154:157], v[226:241]
	ds_read_b128 v[142:145], v132 offset:4608
	s_waitcnt lgkmcnt(3)
	v_mfma_f32_32x32x16_bf16 v[226:241], v[250:253], v[158:161], v[226:241]
	ds_read_b128 v[250:253], v132 offset:6656
	s_waitcnt lgkmcnt(3)
	v_mfma_f32_32x32x16_bf16 v[2:17], v[128:131], v[146:149], v[98:113]
	ds_read_b64_tr_b16 v[128:129], v133
	ds_read_b64_tr_b16 v[130:131], v133 offset:512
	s_waitcnt lgkmcnt(4)
	v_mfma_f32_32x32x16_bf16 v[2:17], v[138:141], v[150:153], v[2:17]
	ds_read_b64_tr_b16 v[138:139], v133 offset:4096
	ds_read_b64_tr_b16 v[140:141], v133 offset:4608
	s_waitcnt lgkmcnt(5)
	v_mfma_f32_32x32x16_bf16 v[2:17], v[142:145], v[154:157], v[2:17]
	ds_read_b64_tr_b16 v[142:143], v133 offset:8192
	ds_read_b64_tr_b16 v[144:145], v133 offset:8704
	s_waitcnt lgkmcnt(6)
	v_mfma_f32_32x32x16_bf16 v[2:17], v[250:253], v[158:161], v[2:17]
	ds_read_b64_tr_b16 v[250:251], v133 offset:12288
	ds_read_b64_tr_b16 v[252:253], v133 offset:12800
	s_branch .Latt_fast_pv
.Latt_fast_top:
	s_waitcnt lgkmcnt(3)
	v_mfma_f32_32x32x16_bf16 v[226:241], v[128:131], v[146:149], v[98:113]
	ds_read_b128 v[128:131], v132 offset:512
	v_exp_f32_e32 v2, v2
	v_exp_f32_e32 v3, v3
	v_exp_f32_e32 v4, v4
	v_exp_f32_e32 v5, v5
	v_cvt_pk_bf16_f32 v124, v2, v3
	v_exp_f32_e32 v6, v6
	s_waitcnt lgkmcnt(3)
	v_mfma_f32_32x32x16_bf16 v[226:241], v[138:141], v[150:153], v[226:241]
	ds_read_b128 v[138:141], v132 offset:2560
	v_exp_f32_e32 v7, v7
	v_cvt_pk_bf16_f32 v125, v4, v5
	v_exp_f32_e32 v8, v8
	v_exp_f32_e32 v9, v9
	v_cvt_pk_bf16_f32 v126, v6, v7
	v_cvt_pk_bf16_f32 v127, v8, v9
	s_waitcnt lgkmcnt(3)
	v_mfma_f32_32x32x16_bf16 v[226:241], v[142:145], v[154:157], v[226:241]
	ds_read_b128 v[142:145], v132 offset:4608
	v_exp_f32_e32 v10, v10
	v_exp_f32_e32 v11, v11
	v_exp_f32_e32 v12, v12
	v_exp_f32_e32 v13, v13
	v_cvt_pk_bf16_f32 v120, v10, v11
	v_exp_f32_e32 v14, v14
	s_waitcnt lgkmcnt(3)
	v_mfma_f32_32x32x16_bf16 v[226:241], v[250:253], v[158:161], v[226:241]
	ds_read_b128 v[250:253], v132 offset:6656
	s_add_i32 s10, s57, 0xffff4000
	s_and_b32 s10, s10, 0xc000
	v_add_u32_e32 v133, s10, v185
	v_exp_f32_e32 v15, v15
	v_cvt_pk_bf16_f32 v121, v12, v13
	v_exp_f32_e32 v16, v16
	v_exp_f32_e32 v17, v17
	v_cvt_pk_bf16_f32 v122, v14, v15
	v_cvt_pk_bf16_f32 v123, v16, v17
	s_waitcnt lgkmcnt(3)
	v_mfma_f32_32x32x16_bf16 v[2:17], v[128:131], v[146:149], v[98:113]
	ds_read_b64_tr_b16 v[128:129], v133
	ds_read_b64_tr_b16 v[130:131], v133 offset:512
	s_add_i32 s9, s56, 2
	s_min_u32 s9, s9, s52
	s_lshl_b32 s58, s9, 14
	s_and_b32 s59, s57, 0xc000
	s_add_i32 s59, s59, s53
	s_add_i32 s9, s56, 3
	s_min_u32 s9, s9, s52
	s_lshl_b32 s10, s9, 14
	s_mov_b32 s11, 0
	s_add_u32 s10, s98, s10
	s_addc_u32 s11, s99, 0
	s_add_i32 s9, s57, 0x4000
	s_and_b32 s9, s9, 0xc000
	s_add_i32 s9, s9, s53
	s_waitcnt lgkmcnt(4)
	v_mfma_f32_32x32x16_bf16 v[2:17], v[138:141], v[150:153], v[2:17]
	ds_read_b64_tr_b16 v[138:139], v133 offset:4096
	ds_read_b64_tr_b16 v[140:141], v133 offset:4608
	s_waitcnt lgkmcnt(5)
	v_mfma_f32_32x32x16_bf16 v[2:17], v[142:145], v[154:157], v[2:17]
	ds_read_b64_tr_b16 v[142:143], v133 offset:8192
	ds_read_b64_tr_b16 v[144:145], v133 offset:8704
	s_waitcnt lgkmcnt(6)
	v_mfma_f32_32x32x16_bf16 v[2:17], v[250:253], v[158:161], v[2:17]
	ds_read_b64_tr_b16 v[250:251], v133 offset:12288
	ds_read_b64_tr_b16 v[252:253], v133 offset:12800
; #define LAS __attribute__((address_space(3)))
; __device__ __forceinline__ float xhalf_max(float v) { auto rr = __builtin_amdgcn_permlane32_swap(__float_as_uint(v), __float_as_uint(v), false, false); return fmaxf(__uint_as_float(rr[0]), __uint_as_float(rr[1])); }
; __device__ __forceinline__ float max3a(float a, float b, float c) { float r; asm("v_max3_f32 %0, %1, %2, %3" : "=v"(r) : "v"(a), "v"(b), "v"(c)); return r; }
; #define ATT_VREADK(ks) do { _Pragma("unroll") for (int d_ = 0; d_ < 4; ++d_) { vl[(ks) & 1][d_] = vtr(vb + d_ * 4096 + (ks) * 1024); vh[(ks) & 1][d_] = vtr(vb + d_ * 4096 + (ks) * 1024 + 512); } } while (0)
; __device__ __forceinline__ void att_qs(bf16x8 (&pn)[4], f32x16 (&o)[4], f32x16& osum, f32x16& negm, const bf16x8 (&qf)[4], float& m_hat, ...
;     ...
;     float rm;
;     { float a = max3a(c0[0], c0[1], c0[2]), b = max3a(c1[0], c1[1], c1[2]);
; #pragma unroll
;       for (int r = 3; r < 15; r += 2) { a = max3a(a, c0[r], c0[r + 1]); b = max3a(b, c1[r], c1[r + 1]); }
;       rm = max3a(a, b, c0[15]); rm = max3a(rm, c1[15], c1[15]); }
;     rm = xhalf_max(rm);
;     if (first_tile) {
;         m_hat += rm;
; #pragma unroll
;         for (int r = 0; r < 16; ++r) { c0[r] -= rm; c1[r] -= rm; negm[r] = -m_hat; }
;     } else if (__any(rm > 8.0f)) {
; __device__ __forceinline__ void att_pv(const bf16x8 (&pp)[4], f32x16 (&o)[4], f32x16& osum, const LAS unsigned char* vb) {
;     s16x4 vl[2][4], vh[2][4];
;     ...
;     const bf16x8 ones = (bf16x8){0x3F80, 0x3F80, 0x3F80, 0x3F80, 0x3F80, 0x3F80, 0x3F80, 0x3F80};
;     ATT_VREADK(0);
; #pragma unroll
;     for (int ks = 0; ks < 4; ++ks) {
;         if (ks + 1 < 4) ATT_VREADK(ks + 1);
;         osum = __builtin_amdgcn_mfma_f32_32x32x16_bf16(pp[ks], ones, osum, 0, 0, 0);
; #pragma unroll
;         for (int d = 0; d < 4; ++d) { const int bk = ks & 1;
;             const bf16x8 vf = (bf16x8){vl[bk][d][0], vl[bk][d][1], vl[bk][d][2], vl[bk][d][3], vh[bk][d][0], vh[bk][d][1], vh[bk][d][2], vh[bk][d][3]};
;             o[d] = __builtin_amdgcn_mfma_f32_32x32x16_bf16(pp[ks], vf, o[d], 0, 0, 0); }
;     }
.Latt_fast_pv:
	v_mfma_f32_32x32x16_bf16 v[18:33], v[134:137], v[242:245], v[18:33]
	s_waitcnt lgkmcnt(6)
	v_mfma_f32_32x32x16_bf16 v[34:49], v[134:137], v[128:131], v[34:49]
	ds_read_b64_tr_b16 v[128:129], v133 offset:1024
	ds_read_b64_tr_b16 v[130:131], v133 offset:1536
	s_mov_b32 m0, s9
	s_nop 0
	global_load_lds_dwordx4 v166, s[10:11]
	s_waitcnt lgkmcnt(6)
	v_mfma_f32_32x32x16_bf16 v[50:65], v[134:137], v[138:141], v[50:65]
	ds_read_b64_tr_b16 v[138:139], v133 offset:5120
	ds_read_b64_tr_b16 v[140:141], v133 offset:5632
	s_add_u32 s10, s10, 0x2000
	s_addc_u32 s11, s11, 0
	s_add_i32 m0, s9, 0x2000
	s_nop 0
	global_load_lds_dwordx4 v166, s[10:11]
	s_waitcnt lgkmcnt(6)
	v_mfma_f32_32x32x16_bf16 v[66:81], v[134:137], v[142:145], v[66:81]
	ds_read_b64_tr_b16 v[142:143], v133 offset:9216
	ds_read_b64_tr_b16 v[144:145], v133 offset:9728
	s_add_u32 s10, s98, s58
	s_addc_u32 s11, s99, 0
	s_add_u32 s10, s10, s101
	s_addc_u32 s11, s11, 0
	s_add_i32 m0, s59, 0x10000
	s_nop 0
	global_load_lds_dwordx4 v166, s[10:11]
	s_waitcnt lgkmcnt(6)
	v_mfma_f32_32x32x16_bf16 v[82:97], v[134:137], v[250:253], v[82:97]
	ds_read_b64_tr_b16 v[250:251], v133 offset:13312
	ds_read_b64_tr_b16 v[252:253], v133 offset:13824
	s_add_u32 s10, s10, 0x2000
	s_addc_u32 s11, s11, 0
	s_add_i32 m0, s59, 0x12000
	s_nop 0
	global_load_lds_dwordx4 v166, s[10:11]
	v_mfma_f32_32x32x16_bf16 v[18:33], v[114:117], v[242:245], v[18:33]
	v_max3_f32 v0, v226, v227, v228
	v_max3_f32 v225, v2, v3, v4
	v_max3_f32 v0, v0, v229, v230
	v_max3_f32 v225, v225, v5, v6
	s_waitcnt lgkmcnt(6)
	v_mfma_f32_32x32x16_bf16 v[34:49], v[114:117], v[128:131], v[34:49]
	ds_read_b64_tr_b16 v[128:129], v133 offset:2048
	ds_read_b64_tr_b16 v[130:131], v133 offset:2560
	v_max3_f32 v0, v0, v231, v232
	v_max3_f32 v225, v225, v7, v8
	v_max3_f32 v0, v0, v233, v234
	s_waitcnt lgkmcnt(6)
	v_mfma_f32_32x32x16_bf16 v[50:65], v[114:117], v[138:141], v[50:65]
	ds_read_b64_tr_b16 v[138:139], v133 offset:6144
	ds_read_b64_tr_b16 v[140:141], v133 offset:6656
	v_max3_f32 v225, v225, v9, v10
	v_max3_f32 v0, v0, v235, v236
	v_max3_f32 v225, v225, v11, v12
	s_waitcnt lgkmcnt(6)
	v_mfma_f32_32x32x16_bf16 v[66:81], v[114:117], v[142:145], v[66:81]
	ds_read_b64_tr_b16 v[142:143], v133 offset:10240
	ds_read_b64_tr_b16 v[144:145], v133 offset:10752
	v_max3_f32 v0, v0, v237, v238
	v_max3_f32 v225, v225, v13, v14
	v_max3_f32 v0, v0, v239, v240
	s_waitcnt lgkmcnt(6)
	v_mfma_f32_32x32x16_bf16 v[82:97], v[114:117], v[250:253], v[82:97]
	ds_read_b64_tr_b16 v[250:251], v133 offset:14336
	ds_read_b64_tr_b16 v[252:253], v133 offset:14848
	v_max3_f32 v225, v225, v15, v16
	v_max3_f32 v0, v0, v225, v241
	v_max3_f32 v0, v0, v17, v17
	v_cmp_lt_f32_e32 vcc, s36, v0
	s_cbranch_vccnz .Latt_fast_rescale
	v_mfma_f32_32x32x16_bf16 v[18:33], v[124:127], v[242:245], v[18:33]
	v_exp_f32_e32 v226, v226
	v_exp_f32_e32 v227, v227
	v_exp_f32_e32 v228, v228
	s_waitcnt lgkmcnt(6)
	v_mfma_f32_32x32x16_bf16 v[34:49], v[124:127], v[128:131], v[34:49]
	ds_read_b64_tr_b16 v[128:129], v133 offset:3072
	ds_read_b64_tr_b16 v[130:131], v133 offset:3584
	v_exp_f32_e32 v229, v229
	v_cvt_pk_bf16_f32 v134, v226, v227
	v_exp_f32_e32 v230, v230
	s_waitcnt lgkmcnt(6)
	v_mfma_f32_32x32x16_bf16 v[50:65], v[124:127], v[138:141], v[50:65]
	ds_read_b64_tr_b16 v[138:139], v133 offset:7168
	ds_read_b64_tr_b16 v[140:141], v133 offset:7680
	v_exp_f32_e32 v231, v231
	v_cvt_pk_bf16_f32 v135, v228, v229
	s_waitcnt lgkmcnt(6)
	v_mfma_f32_32x32x16_bf16 v[66:81], v[124:127], v[142:145], v[66:81]
	ds_read_b64_tr_b16 v[142:143], v133 offset:11264
	ds_read_b64_tr_b16 v[144:145], v133 offset:11776
	v_exp_f32_e32 v232, v232
	v_exp_f32_e32 v233, v233
	s_waitcnt lgkmcnt(6)
	v_mfma_f32_32x32x16_bf16 v[82:97], v[124:127], v[250:253], v[82:97]
	ds_read_b64_tr_b16 v[250:251], v133 offset:15360
	ds_read_b64_tr_b16 v[252:253], v133 offset:15872
	v_cvt_pk_bf16_f32 v136, v230, v231
	v_cvt_pk_bf16_f32 v137, v232, v233
	v_mfma_f32_32x32x16_bf16 v[18:33], v[120:123], v[242:245], v[18:33]
	v_exp_f32_e32 v234, v234
	v_exp_f32_e32 v235, v235
	v_exp_f32_e32 v236, v236
	s_waitcnt lgkmcnt(6)
	v_mfma_f32_32x32x16_bf16 v[34:49], v[120:123], v[128:131], v[34:49]
	s_add_i32 s9, s57, 0xffffc000
	s_and_b32 s9, s9, 0xc000
	v_add_u32_e32 v132, s9, v177
	ds_read_b128 v[128:131], v132
	v_exp_f32_e32 v237, v237
	v_cvt_pk_bf16_f32 v114, v234, v235
	v_exp_f32_e32 v238, v238
	s_waitcnt lgkmcnt(5)
	v_mfma_f32_32x32x16_bf16 v[50:65], v[120:123], v[138:141], v[50:65]
	ds_read_b128 v[138:141], v132 offset:2048
	s_add_i32 s56, s56, 1
	s_addk_i32 s57, 0x4000
	s_add_i32 s55, s55, 64
	s_cmp_lg_u32 s50, s56
	s_cselect_b32 s16, 1, 0
	s_cmp_le_u32 s56, s54
	s_cselect_b32 s16, s16, 0
	s_cmpk_lt_i32 s55, 0xffa6
	s_cselect_b32 s16, s16, 0
	v_exp_f32_e32 v239, v239
	v_cvt_pk_bf16_f32 v115, v236, v237
	v_exp_f32_e32 v240, v240
	s_waitcnt lgkmcnt(4)
	v_mfma_f32_32x32x16_bf16 v[66:81], v[120:123], v[142:145], v[66:81]
	ds_read_b128 v[142:145], v132 offset:4096
	v_exp_f32_e32 v241, v241
	v_cvt_pk_bf16_f32 v116, v238, v239
	v_cvt_pk_bf16_f32 v117, v240, v241
	s_waitcnt lgkmcnt(3)
	v_mfma_f32_32x32x16_bf16 v[82:97], v[120:123], v[250:253], v[82:97]
	ds_read_b128 v[250:253], v132 offset:6144

; __device__ __forceinline__ unsigned pk2(float lo, float hi) { f32x2_t v = {lo, hi}; bf16x2_t b = __builtin_convertvector(v, bf16x2_t); return __builtin_bit_cast(unsigned, b); }
; __device__ __forceinline__ void att_qs(bf16x8 (&pn)[4], f32x16 (&o)[4], f32x16& osum, f32x16& negm, const bf16x8 (&qf)[4], float& m_hat, ...
;     ...
;     unsigned paw[16];
; #pragma unroll
;     for (int g = 0; g < 8; ++g) { const int b = (4 * g) & 15;
;         const float v0 = __builtin_amdgcn_exp2f(g < 4 ? c0[b] : c1[b]), v1 = __builtin_amdgcn_exp2f(g < 4 ? c0[b + 1] : c1[b + 1]);
;         const float v2 = __builtin_amdgcn_exp2f(g < 4 ? c0[b + 2] : c1[b + 2]), v3 = __builtin_amdgcn_exp2f(g < 4 ? c0[b + 3] : c1[b + 3]);
;         paw[2 * g] = pk2(v0, v1); paw[2 * g + 1] = pk2(v2, v3); }
; #pragma unroll
;     for (int k = 0; k < 4; ++k) { u32x4 w; w.x = paw[4 * k]; w.y = paw[4 * k + 1]; w.z = paw[4 * k + 2]; w.w = paw[4 * k + 3]; pn[k] = __builtin_bit_cast(bf16x8, w); }
.Latt_fast_exit:
	s_waitcnt lgkmcnt(0)
	v_exp_f32_e32 v2, v2
	v_exp_f32_e32 v3, v3
	v_exp_f32_e32 v4, v4
	v_exp_f32_e32 v5, v5
	v_cvt_pk_bf16_f32 v124, v2, v3
	v_exp_f32_e32 v6, v6
	v_exp_f32_e32 v7, v7
	v_cvt_pk_bf16_f32 v125, v4, v5
	v_exp_f32_e32 v8, v8
	v_exp_f32_e32 v9, v9
	v_cvt_pk_bf16_f32 v126, v6, v7
	v_cvt_pk_bf16_f32 v127, v8, v9
	v_exp_f32_e32 v10, v10
	v_exp_f32_e32 v11, v11
	v_exp_f32_e32 v12, v12
	v_exp_f32_e32 v13, v13
	v_cvt_pk_bf16_f32 v120, v10, v11
	v_exp_f32_e32 v14, v14
	v_exp_f32_e32 v15, v15
	v_cvt_pk_bf16_f32 v121, v12, v13
	v_exp_f32_e32 v16, v16
	v_exp_f32_e32 v17, v17
	v_cvt_pk_bf16_f32 v122, v14, v15
	v_cvt_pk_bf16_f32 v123, v16, v17
	v_mov_b32_e32 v17, v248
	v_mov_b32_e32 v16, v118
	s_cmp_eq_u32 s50, s56
	s_cbranch_scc1 .LBB0_693
	s_branch .Latt_old_iter
; #define LAS __attribute__((address_space(3)))
; __device__ __forceinline__ int crow(int r, int hi) { return (r & 3) + 8 * (r >> 2) + 4 * hi; }
; #define ATT_VREADK(ks) do { _Pragma("unroll") for (int d_ = 0; d_ < 4; ++d_) { vl[(ks) & 1][d_] = vtr(vb + d_ * 4096 + (ks) * 1024); vh[(ks) & 1][d_] = vtr(vb + d_ * 4096 + (ks) * 1024 + 512); } } while (0)
; __device__ __forceinline__ void att_qs(bf16x8 (&pn)[4], f32x16 (&o)[4], f32x16& osum, f32x16& negm, const bf16x8 (&qf)[4], float& m_hat, ...
;     ...
;     } else if (__any(rm > 8.0f)) {
;         const float dl = fmaxf(rm, 0.f); m_hat += dl; const float f = __builtin_amdgcn_exp2f(-dl);
; #pragma unroll
;         for (int r = 0; r < 16; ++r) { c0[r] -= dl; c1[r] -= dl; negm[r] = -m_hat; }
;         if (hi == 0) scr[i32] = f;
;         asm volatile("s_waitcnt lgkmcnt(0)" ::: "memory");
; #pragma unroll
;         for (int r = 0; r < 16; ++r) { const float fr_ = scr[crow(r, hi)]; osum[r] *= fr_;
; #pragma unroll
;             for (int d = 0; d < 4; ++d) o[d][r] *= fr_; }
;     }
; __device__ __forceinline__ void att_pv(const bf16x8 (&pp)[4], f32x16 (&o)[4], f32x16& osum, const LAS unsigned char* vb) {
;     s16x4 vl[2][4], vh[2][4];
;     ...
;     const bf16x8 ones = (bf16x8){0x3F80, 0x3F80, 0x3F80, 0x3F80, 0x3F80, 0x3F80, 0x3F80, 0x3F80};
;     ATT_VREADK(0);
; #pragma unroll
;     for (int ks = 0; ks < 4; ++ks) {
;         if (ks + 1 < 4) ATT_VREADK(ks + 1);
;         osum = __builtin_amdgcn_mfma_f32_32x32x16_bf16(pp[ks], ones, osum, 0, 0, 0);
; #pragma unroll
;         for (int d = 0; d < 4; ++d) { const int bk = ks & 1;
;             const bf16x8 vf = (bf16x8){vl[bk][d][0], vl[bk][d][1], vl[bk][d][2], vl[bk][d][3], vh[bk][d][0], vh[bk][d][1], vh[bk][d][2], vh[bk][d][3]};
;             o[d] = __builtin_amdgcn_mfma_f32_32x32x16_bf16(pp[ks], vf, o[d], 0, 0, 0); }
;     }
.Latt_fast_rescale:
	s_waitcnt lgkmcnt(0)
	v_mfma_f32_32x32x16_bf16 v[18:33], v[124:127], v[242:245], v[18:33]
	v_mfma_f32_32x32x16_bf16 v[34:49], v[124:127], v[128:131], v[34:49]
	v_mfma_f32_32x32x16_bf16 v[50:65], v[124:127], v[138:141], v[50:65]
	v_mfma_f32_32x32x16_bf16 v[66:81], v[124:127], v[142:145], v[66:81]
	v_mfma_f32_32x32x16_bf16 v[82:97], v[124:127], v[250:253], v[82:97]
	ds_read_b64_tr_b16 v[128:129], v133 offset:3072
	ds_read_b64_tr_b16 v[130:131], v133 offset:3584
	ds_read_b64_tr_b16 v[138:139], v133 offset:7168
	ds_read_b64_tr_b16 v[140:141], v133 offset:7680
	ds_read_b64_tr_b16 v[142:143], v133 offset:11264
	ds_read_b64_tr_b16 v[144:145], v133 offset:11776
	ds_read_b64_tr_b16 v[250:251], v133 offset:15360
	ds_read_b64_tr_b16 v[252:253], v133 offset:15872
	s_waitcnt lgkmcnt(0)
	v_mfma_f32_32x32x16_bf16 v[18:33], v[120:123], v[242:245], v[18:33]
	v_mfma_f32_32x32x16_bf16 v[34:49], v[120:123], v[128:131], v[34:49]
	v_mfma_f32_32x32x16_bf16 v[50:65], v[120:123], v[138:141], v[50:65]
	v_mfma_f32_32x32x16_bf16 v[66:81], v[120:123], v[142:145], v[66:81]
	v_mfma_f32_32x32x16_bf16 v[82:97], v[120:123], v[250:253], v[82:97]
	s_nop 15
	v_mov_b32_e32 v225, v0
	s_nop 1
	v_permlane32_swap_b32_e32 v0, v225
	v_max_f32_e32 v0, v0, v225
	v_max_f32_e32 v0, 0, v0
	v_add_f32_e32 v248, v248, v0
	v_exp_f32_e64 v225, -v0
	s_and_saveexec_b64 s[10:11], s[6:7]
	ds_write_b32 v224, v225
	s_or_b64 exec, exec, s[10:11]
	s_waitcnt lgkmcnt(0)
	v_add_u32_e32 v132, s51, v187
	ds_read_b128 v[128:131], v132
	ds_read_b128 v[138:141], v132 offset:32
	ds_read_b128 v[142:145], v132 offset:64
	ds_read_b128 v[250:253], v132 offset:96
	v_sub_f32_e32 v226, v226, v0
	v_sub_f32_e32 v227, v227, v0
	v_sub_f32_e32 v228, v228, v0
	v_sub_f32_e32 v229, v229, v0
	v_sub_f32_e32 v230, v230, v0
	v_sub_f32_e32 v231, v231, v0
	v_sub_f32_e32 v232, v232, v0
	v_sub_f32_e32 v233, v233, v0
	v_sub_f32_e32 v234, v234, v0
	v_sub_f32_e32 v235, v235, v0
	v_sub_f32_e32 v236, v236, v0
	v_sub_f32_e32 v237, v237, v0
	v_sub_f32_e32 v238, v238, v0
	v_sub_f32_e32 v239, v239, v0
	v_sub_f32_e32 v240, v240, v0
	v_sub_f32_e32 v241, v241, v0
	v_sub_f32_e32 v2, v2, v0
	v_sub_f32_e32 v3, v3, v0
	v_sub_f32_e32 v4, v4, v0
	v_sub_f32_e32 v5, v5, v0
	v_sub_f32_e32 v6, v6, v0
	v_sub_f32_e32 v7, v7, v0
	v_sub_f32_e32 v8, v8, v0
	v_sub_f32_e32 v9, v9, v0
	v_sub_f32_e32 v10, v10, v0
	v_sub_f32_e32 v11, v11, v0
	v_sub_f32_e32 v12, v12, v0
	v_sub_f32_e32 v13, v13, v0
	v_sub_f32_e32 v14, v14, v0
	v_sub_f32_e32 v15, v15, v0
	v_sub_f32_e32 v16, v16, v0
	v_sub_f32_e32 v17, v17, v0
	v_xor_b32_e32 v98, 0x80000000, v248
	v_mov_b32_e32 v99, v98
	v_mov_b32_e32 v100, v98
	v_mov_b32_e32 v101, v98
	v_mov_b32_e32 v102, v98
	v_mov_b32_e32 v103, v98
	v_mov_b32_e32 v104, v98
	v_mov_b32_e32 v105, v98
	v_mov_b32_e32 v106, v98
	v_mov_b32_e32 v107, v98
	v_mov_b32_e32 v108, v98
	v_mov_b32_e32 v109, v98
	v_mov_b32_e32 v110, v98
	v_mov_b32_e32 v111, v98
	v_mov_b32_e32 v112, v98
	v_mov_b32_e32 v113, v98
	s_waitcnt lgkmcnt(0)
	v_mul_f32_e32 v18, v18, v128
	v_mul_f32_e32 v34, v34, v128
	v_mul_f32_e32 v50, v50, v128
	v_mul_f32_e32 v66, v66, v128
	v_mul_f32_e32 v82, v82, v128
	v_mul_f32_e32 v19, v19, v129
	v_mul_f32_e32 v35, v35, v129
	v_mul_f32_e32 v51, v51, v129
	v_mul_f32_e32 v67, v67, v129
	v_mul_f32_e32 v83, v83, v129
	v_mul_f32_e32 v20, v20, v130
	v_mul_f32_e32 v36, v36, v130
	v_mul_f32_e32 v52, v52, v130
	v_mul_f32_e32 v68, v68, v130
	v_mul_f32_e32 v84, v84, v130
	v_mul_f32_e32 v21, v21, v131
	v_mul_f32_e32 v37, v37, v131
	v_mul_f32_e32 v53, v53, v131
	v_mul_f32_e32 v69, v69, v131
	v_mul_f32_e32 v85, v85, v131
	v_mul_f32_e32 v22, v22, v138
	v_mul_f32_e32 v38, v38, v138
	v_mul_f32_e32 v54, v54, v138
	v_mul_f32_e32 v70, v70, v138
	v_mul_f32_e32 v86, v86, v138
	v_mul_f32_e32 v23, v23, v139
	v_mul_f32_e32 v39, v39, v139
	v_mul_f32_e32 v55, v55, v139
	v_mul_f32_e32 v71, v71, v139
	v_mul_f32_e32 v87, v87, v139
	v_mul_f32_e32 v24, v24, v140
	v_mul_f32_e32 v40, v40, v140
	v_mul_f32_e32 v56, v56, v140
	v_mul_f32_e32 v72, v72, v140
	v_mul_f32_e32 v88, v88, v140
	v_mul_f32_e32 v25, v25, v141
	v_mul_f32_e32 v41, v41, v141
	v_mul_f32_e32 v57, v57, v141
	v_mul_f32_e32 v73, v73, v141
	v_mul_f32_e32 v89, v89, v141
	v_mul_f32_e32 v26, v26, v142
	v_mul_f32_e32 v42, v42, v142
	v_mul_f32_e32 v58, v58, v142
	v_mul_f32_e32 v74, v74, v142
	v_mul_f32_e32 v90, v90, v142
	v_mul_f32_e32 v27, v27, v143
	v_mul_f32_e32 v43, v43, v143
	v_mul_f32_e32 v59, v59, v143
	v_mul_f32_e32 v75, v75, v143
	v_mul_f32_e32 v91, v91, v143
	v_mul_f32_e32 v28, v28, v144
	v_mul_f32_e32 v44, v44, v144
	v_mul_f32_e32 v60, v60, v144
	v_mul_f32_e32 v76, v76, v144
	v_mul_f32_e32 v92, v92, v144
	v_mul_f32_e32 v29, v29, v145
	v_mul_f32_e32 v45, v45, v145
	v_mul_f32_e32 v61, v61, v145
	v_mul_f32_e32 v77, v77, v145
	v_mul_f32_e32 v93, v93, v145
	v_mul_f32_e32 v30, v30, v250
	v_mul_f32_e32 v46, v46, v250
	v_mul_f32_e32 v62, v62, v250
	v_mul_f32_e32 v78, v78, v250
	v_mul_f32_e32 v94, v94, v250
	v_mul_f32_e32 v31, v31, v251
	v_mul_f32_e32 v47, v47, v251
	v_mul_f32_e32 v63, v63, v251
	v_mul_f32_e32 v79, v79, v251
	v_mul_f32_e32 v95, v95, v251
	v_mul_f32_e32 v32, v32, v252
	v_mul_f32_e32 v48, v48, v252
	v_mul_f32_e32 v64, v64, v252
	v_mul_f32_e32 v80, v80, v252
	v_mul_f32_e32 v96, v96, v252
	v_mul_f32_e32 v33, v33, v253
	v_mul_f32_e32 v49, v49, v253
	v_mul_f32_e32 v65, v65, v253
	v_mul_f32_e32 v81, v81, v253
	v_mul_f32_e32 v97, v97, v253
	v_exp_f32_e32 v226, v226
	v_exp_f32_e32 v227, v227
	v_exp_f32_e32 v228, v228
	v_exp_f32_e32 v229, v229
	v_cvt_pk_bf16_f32 v134, v226, v227
	v_exp_f32_e32 v230, v230
	v_exp_f32_e32 v231, v231
	v_cvt_pk_bf16_f32 v135, v228, v229
	v_exp_f32_e32 v232, v232
	v_exp_f32_e32 v233, v233
	v_cvt_pk_bf16_f32 v136, v230, v231
	v_cvt_pk_bf16_f32 v137, v232, v233
	v_exp_f32_e32 v234, v234
	v_exp_f32_e32 v235, v235
	v_exp_f32_e32 v236, v236
	v_exp_f32_e32 v237, v237
	v_cvt_pk_bf16_f32 v114, v234, v235
	v_exp_f32_e32 v238, v238
	v_exp_f32_e32 v239, v239
	v_cvt_pk_bf16_f32 v115, v236, v237
	v_exp_f32_e32 v240, v240
	v_exp_f32_e32 v241, v241
	v_cvt_pk_bf16_f32 v116, v238, v239
	v_cvt_pk_bf16_f32 v117, v240, v241
	s_waitcnt lgkmcnt(0)
	s_add_i32 s9, s57, 0xffffc000
	s_and_b32 s9, s9, 0xc000
	v_add_u32_e32 v132, s9, v177
	ds_read_b128 v[128:131], v132
	ds_read_b128 v[138:141], v132 offset:2048
	ds_read_b128 v[142:145], v132 offset:4096
	ds_read_b128 v[250:253], v132 offset:6144
	s_add_i32 s56, s56, 1
	s_addk_i32 s57, 0x4000
	s_add_i32 s55, s55, 64
	s_cmp_lg_u32 s50, s56
	s_cselect_b32 s16, 1, 0
	s_cmp_le_u32 s56, s54
	s_cselect_b32 s16, s16, 0
	s_cmpk_lt_i32 s55, 0xffa6
	s_cselect_b32 s16, s16, 0
	s_branch .Latt_fast_end
